# fin2_pad + attention step barrier moved up to right after PV's final LDS wait (12 register-only MFMAs trail the barrier)
# baseline (speedup 1.0000x reference)
.LBB0_400:
	v_cvt_pk_bf16_f32 v182, v148, v149
	v_cvt_pk_bf16_f32 v183, v152, v153
	v_cvt_pk_bf16_f32 v184, v154, v155
	v_cvt_pk_bf16_f32 v185, v158, v159
	v_cvt_pk_bf16_f32 v160, v150, v151
	v_cvt_pk_bf16_f32 v161, v156, v157
	v_cvt_pk_bf16_f32 v162, v162, v163
	v_cvt_pk_bf16_f32 v163, v166, v167
	s_waitcnt vmcnt(0)
	ds_write_b128 v205, v[132:135]
	ds_write_b128 v206, v[136:139]
	ds_write_b128 v207, v[128:131] offset:32768
	s_cmpk_lt_u32 s51, 0x100
	s_cselect_b32 s0, s38, s34
	s_add_i32 s3, s0, s51
	s_mul_i32 s0, s3, 0x1800
	s_mul_hi_i32 s1, s3, 0x1800
	s_add_u32 s0, s39, s0
	s_addc_u32 s1, s42, s1
	v_lshl_add_u64 v[148:149], s[0:1], 0, v[170:171]
	v_add_co_u32_e32 v152, vcc, s33, v148
	v_mad_i64_i32 v[156:157], s[0:1], s3, v195, v[180:181]
	s_nop 0
	v_addc_co_u32_e32 v153, vcc, 0, v149, vcc
	global_load_dwordx4 v[148:151], v[148:149], off
	s_nop 0
	global_load_dwordx4 v[152:155], v[152:153], off
	s_nop 0
	global_load_dwordx4 v[156:159], v[156:157], off
	ds_read_b64_tr_b16 v[186:187], v203 offset:0
	ds_read_b64_tr_b16 v[188:189], v203 offset:0x800
	ds_read_b64_tr_b16 v[214:215], v203 offset:0x200
	ds_read_b64_tr_b16 v[216:217], v203 offset:0xa00
	ds_read_b64_tr_b16 v[218:219], v203 offset:0x400
	ds_read_b64_tr_b16 v[220:221], v203 offset:0xc00
	ds_read_b64_tr_b16 v[222:223], v203 offset:0x600
	ds_read_b64_tr_b16 v[224:225], v203 offset:0xe00
	ds_read_b64_tr_b16 v[226:227], v203 offset:0x1000
	ds_read_b64_tr_b16 v[228:229], v203 offset:0x1800
	ds_read_b64_tr_b16 v[230:231], v203 offset:0x1200
	ds_read_b64_tr_b16 v[232:233], v203 offset:0x1a00
	ds_read_b64_tr_b16 v[234:235], v203 offset:0x1400
	ds_read_b64_tr_b16 v[236:237], v203 offset:0x1c00
	ds_read_b64_tr_b16 v[238:239], v203 offset:0x1600
	ds_read_b64_tr_b16 v[240:241], v203 offset:0x1e00
	s_nop 0
	s_waitcnt lgkmcnt(8)
	v_exp_f32_e32 v112, v112
	v_mfma_f32_32x32x16_bf16 v[0:15], v[144:147], v[186:189], v[0:15]
	v_exp_f32_e32 v113, v113
	v_exp_f32_e32 v114, v114
	v_exp_f32_e32 v115, v115
	v_exp_f32_e32 v116, v116
	v_exp_f32_e32 v117, v117
	v_exp_f32_e32 v118, v118
	v_exp_f32_e32 v119, v119
	v_mfma_f32_32x32x16_bf16 v[48:63], v[144:147], v[214:217], v[48:63]
	v_exp_f32_e32 v120, v120
	v_exp_f32_e32 v121, v121
	v_exp_f32_e32 v122, v122
	v_exp_f32_e32 v123, v123
	v_exp_f32_e32 v124, v124
	v_exp_f32_e32 v125, v125
	v_exp_f32_e32 v126, v126
	v_mfma_f32_32x32x16_bf16 v[32:47], v[144:147], v[218:221], v[32:47]
	v_exp_f32_e32 v127, v127
	v_mfma_f32_32x32x16_bf16 v[16:31], v[144:147], v[222:225], v[16:31]
	ds_read_b64_tr_b16 v[144:145], v203 offset:0x2000
	ds_read_b64_tr_b16 v[146:147], v203 offset:0x2800
	ds_read_b64_tr_b16 v[186:187], v203 offset:0x2200
	ds_read_b64_tr_b16 v[188:189], v203 offset:0x2a00
	ds_read_b64_tr_b16 v[214:215], v203 offset:0x2400
	ds_read_b64_tr_b16 v[216:217], v203 offset:0x2c00
	ds_read_b64_tr_b16 v[218:219], v203 offset:0x2600
	ds_read_b64_tr_b16 v[220:221], v203 offset:0x2e00
	s_waitcnt lgkmcnt(8)
	ds_read_b64_tr_b16 v[222:223], v203 offset:0x3000
	ds_read_b64_tr_b16 v[224:225], v203 offset:0x3800
	s_nop 0
	v_mfma_f32_32x32x16_bf16 v[0:15], v[140:143], v[226:229], v[0:15]
	ds_read_b64_tr_b16 v[226:227], v203 offset:0x3200
	ds_read_b64_tr_b16 v[228:229], v203 offset:0x3a00
	v_mfma_f32_32x32x16_bf16 v[48:63], v[140:143], v[230:233], v[48:63]
	ds_read_b64_tr_b16 v[230:231], v203 offset:0x3400
	ds_read_b64_tr_b16 v[232:233], v203 offset:0x3c00
	v_mfma_f32_32x32x16_bf16 v[32:47], v[140:143], v[234:237], v[32:47]
	ds_read_b64_tr_b16 v[234:235], v203 offset:0x3600
	ds_read_b64_tr_b16 v[236:237], v203 offset:0x3e00
	s_waitcnt lgkmcnt(8)
	s_nop 0
	s_waitcnt lgkmcnt(0)
	s_barrier
	v_mfma_f32_32x32x16_bf16 v[16:31], v[140:143], v[238:241], v[16:31]
	v_add_f32_e32 v140, 0, v112
	v_add_f32_e32 v140, v113, v140
	v_add_f32_e32 v140, v114, v140
	v_add_f32_e32 v140, v115, v140
	v_add_f32_e32 v140, v116, v140
	v_add_f32_e32 v140, v117, v140
	v_add_f32_e32 v140, v118, v140
	v_mfma_f32_32x32x16_bf16 v[0:15], v[182:185], v[144:147], v[0:15]
	v_add_f32_e32 v140, v119, v140
	v_add_f32_e32 v140, v120, v140
	v_add_f32_e32 v140, v121, v140
	v_add_f32_e32 v140, v122, v140
	v_add_f32_e32 v140, v123, v140
	v_add_f32_e32 v140, v124, v140
	v_add_f32_e32 v140, v125, v140
	v_mfma_f32_32x32x16_bf16 v[48:63], v[182:185], v[186:189], v[48:63]
	v_add_f32_e32 v140, v126, v140
	v_add_f32_e32 v165, v127, v140
	v_cvt_pk_bf16_f32 v144, v112, v113
	v_cvt_pk_bf16_f32 v145, v114, v115
	v_cvt_pk_bf16_f32 v146, v116, v117
	v_cvt_pk_bf16_f32 v147, v118, v119
	v_cvt_pk_bf16_f32 v140, v120, v121
	v_mfma_f32_32x32x16_bf16 v[32:47], v[182:185], v[214:217], v[32:47]
	v_cvt_pk_bf16_f32 v141, v122, v123
	v_cvt_pk_bf16_f32 v142, v124, v125
	v_cvt_pk_bf16_f32 v143, v126, v127
	v_mfma_f32_32x32x16_bf16 v[16:31], v[182:185], v[218:221], v[16:31]
	v_mfma_f32_32x32x16_bf16 v[0:15], v[160:163], v[222:225], v[0:15]
	v_mfma_f32_32x32x16_bf16 v[48:63], v[160:163], v[226:229], v[48:63]
	v_mfma_f32_32x32x16_bf16 v[32:47], v[160:163], v[230:233], v[32:47]
	v_mfma_f32_32x32x16_bf16 v[16:31], v[160:163], v[234:237], v[16:31]
	v_add_u32_e32 v208, s101, v208
	v_add_u32_e32 v209, s101, v209
	v_add_u32_e32 v210, s101, v210
	v_add_u32_e32 v211, s101, v211
	ds_read_b128 v[160:163], v208 offset:32768
	ds_read_b128 v[214:217], v204 offset:51200
	ds_read_b128 v[218:221], v204 offset:52224
	ds_read_b128 v[222:225], v208 offset:36864
	v_exp_f32_e32 v166, v84
	v_exp_f32_e32 v167, v85
	s_waitcnt lgkmcnt(2)
	v_mfma_f32_32x32x16_bf16 v[112:127], v[160:163], v[214:217], v[96:111]
	ds_read_b128 v[160:163], v209 offset:32768
	ds_read_b128 v[226:229], v209 offset:36864
	ds_read_b128 v[230:233], v204 offset:53248
	ds_read_b128 v[234:237], v204 offset:54272
	ds_read_b128 v[238:241], v210 offset:36864
	ds_read_b128 v[182:185], v210 offset:32768
	ds_read_b128 v[242:245], v211 offset:36864
	ds_read_b128 v[188:191], v211 offset:32768
	v_exp_f32_e32 v186, v90
	v_exp_f32_e32 v187, v91
	s_andn2_b64 s[0:1], s[6:7], exec
	s_and_b64 s[6:7], s[8:9], exec
	s_or_b64 s[6:7], s[0:1], s[6:7]
	s_waitcnt lgkmcnt(7)
	v_mfma_f32_32x32x16_bf16 v[112:127], v[160:163], v[218:221], v[112:127]
	v_exp_f32_e32 v160, v80
	v_exp_f32_e32 v161, v81
	v_exp_f32_e32 v162, v82
	v_exp_f32_e32 v163, v83
	v_add_f32_e32 v80, v160, v165
	v_add_f32_e32 v80, v161, v80
	v_add_f32_e32 v165, v162, v80
	s_waitcnt lgkmcnt(2)
	v_mfma_f32_32x32x16_bf16 v[112:127], v[182:185], v[230:233], v[112:127]
	v_exp_f32_e32 v182, v86
	v_exp_f32_e32 v183, v87
	v_exp_f32_e32 v184, v88
	v_exp_f32_e32 v185, v89
	v_add_f32_e32 v165, v163, v165
	v_add_f32_e32 v165, v166, v165
	v_add_f32_e32 v165, v167, v165
	s_waitcnt lgkmcnt(0)
	v_mfma_f32_32x32x16_bf16 v[112:127], v[188:191], v[234:237], v[112:127]
	v_exp_f32_e32 v188, v92
	v_exp_f32_e32 v189, v93
	v_exp_f32_e32 v190, v94
	v_exp_f32_e32 v191, v95
	v_add_f32_e32 v165, v182, v165
	v_add_f32_e32 v165, v183, v165
	v_add_f32_e32 v165, v184, v165
	v_mfma_f32_32x32x16_bf16 v[80:95], v[222:225], v[214:217], v[96:111]
	v_add_f32_e32 v165, v185, v165
	v_add_f32_e32 v165, v186, v165
	v_add_f32_e32 v165, v187, v165
	v_add_f32_e32 v165, v188, v165
	v_add_f32_e32 v165, v189, v165
	v_add_f32_e32 v165, v190, v165
	v_add_f32_e32 v165, v191, v165
	v_mfma_f32_32x32x16_bf16 v[80:95], v[226:229], v[218:221], v[80:95]
	v_mov_b32_e32 v179, v165
	s_nop 1
	v_permlane32_swap_b32_e32 v165, v179
	v_add_f32_e64 v178, v164, v178
	v_add_f32_e64 v179, v165, v179
	v_cmp_ge_f32_e32 vcc, s99, v179
	s_cmp_eq_u64 vcc, exec
	v_mfma_f32_32x32x16_bf16 v[80:95], v[238:241], v[230:233], v[80:95]
	v_mfma_f32_32x32x16_bf16 v[80:95], v[242:245], v[234:237], v[80:95]
	s_cbranch_scc0 .LBB0_408

.LBB0_403:
	v_add_f32_e32 v178, v179, v178
	ds_read_b64_tr_b16 v[182:183], v202 offset:0
	ds_read_b64_tr_b16 v[184:185], v202 offset:0x800
	ds_read_b64_tr_b16 v[186:187], v202 offset:0x200
	ds_read_b64_tr_b16 v[188:189], v202 offset:0xa00
	ds_read_b64_tr_b16 v[214:215], v202 offset:0x400
	ds_read_b64_tr_b16 v[216:217], v202 offset:0xc00
	ds_read_b64_tr_b16 v[218:219], v202 offset:0x600
	ds_read_b64_tr_b16 v[220:221], v202 offset:0xe00
	ds_read_b64_tr_b16 v[222:223], v202 offset:0x1000
	ds_read_b64_tr_b16 v[224:225], v202 offset:0x1800
	ds_read_b64_tr_b16 v[226:227], v202 offset:0x1200
	ds_read_b64_tr_b16 v[228:229], v202 offset:0x1a00
	ds_read_b64_tr_b16 v[230:231], v202 offset:0x1400
	ds_read_b64_tr_b16 v[232:233], v202 offset:0x1c00
	ds_read_b64_tr_b16 v[234:235], v202 offset:0x1600
	ds_read_b64_tr_b16 v[236:237], v202 offset:0x1e00
	s_nop 0
	s_waitcnt lgkmcnt(8)
	v_exp_f32_e32 v112, v112
	v_mfma_f32_32x32x16_bf16 v[0:15], v[144:147], v[182:185], v[0:15]
	v_exp_f32_e32 v113, v113
	v_exp_f32_e32 v114, v114
	v_exp_f32_e32 v115, v115
	v_exp_f32_e32 v116, v116
	v_exp_f32_e32 v117, v117
	v_exp_f32_e32 v118, v118
	v_exp_f32_e32 v119, v119
	v_mfma_f32_32x32x16_bf16 v[48:63], v[144:147], v[186:189], v[48:63]
	v_exp_f32_e32 v120, v120
	v_exp_f32_e32 v121, v121
	v_exp_f32_e32 v122, v122
	v_exp_f32_e32 v123, v123
	v_exp_f32_e32 v124, v124
	v_exp_f32_e32 v125, v125
	v_exp_f32_e32 v126, v126
	v_mfma_f32_32x32x16_bf16 v[32:47], v[144:147], v[214:217], v[32:47]
	v_exp_f32_e32 v127, v127
	s_addk_i32 s51, 0x80
	s_add_i32 s50, s50, 2
	s_and_b64 vcc, exec, s[8:9]
	v_mfma_f32_32x32x16_bf16 v[16:31], v[144:147], v[218:221], v[16:31]
	ds_read_b64_tr_b16 v[144:145], v202 offset:0x2000
	ds_read_b64_tr_b16 v[146:147], v202 offset:0x2800
	ds_read_b64_tr_b16 v[182:183], v202 offset:0x2200
	ds_read_b64_tr_b16 v[184:185], v202 offset:0x2a00
	ds_read_b64_tr_b16 v[186:187], v202 offset:0x2400
	ds_read_b64_tr_b16 v[188:189], v202 offset:0x2c00
	ds_read_b64_tr_b16 v[214:215], v202 offset:0x2600
	ds_read_b64_tr_b16 v[216:217], v202 offset:0x2e00
	s_waitcnt lgkmcnt(8)
	ds_read_b64_tr_b16 v[218:219], v202 offset:0x3000
	ds_read_b64_tr_b16 v[220:221], v202 offset:0x3800
	s_nop 0
	v_mfma_f32_32x32x16_bf16 v[0:15], v[140:143], v[222:225], v[0:15]
	ds_read_b64_tr_b16 v[222:223], v202 offset:0x3200
	ds_read_b64_tr_b16 v[224:225], v202 offset:0x3a00
	v_mfma_f32_32x32x16_bf16 v[48:63], v[140:143], v[226:229], v[48:63]
	ds_read_b64_tr_b16 v[226:227], v202 offset:0x3400
	ds_read_b64_tr_b16 v[228:229], v202 offset:0x3c00
	v_mfma_f32_32x32x16_bf16 v[32:47], v[140:143], v[230:233], v[32:47]
	ds_read_b64_tr_b16 v[230:231], v202 offset:0x3600
	ds_read_b64_tr_b16 v[232:233], v202 offset:0x3e00
	s_waitcnt lgkmcnt(8)
	s_nop 0
	s_waitcnt lgkmcnt(0)
	s_barrier
	v_mfma_f32_32x32x16_bf16 v[16:31], v[140:143], v[234:237], v[16:31]
	v_add_f32_e32 v140, 0, v112
	v_add_f32_e32 v140, v113, v140
	v_add_f32_e32 v140, v114, v140
	v_add_f32_e32 v140, v115, v140
	v_add_f32_e32 v140, v116, v140
	v_add_f32_e32 v140, v117, v140
	v_add_f32_e32 v140, v118, v140
	v_mfma_f32_32x32x16_bf16 v[0:15], v[164:167], v[144:147], v[0:15]
	v_add_f32_e32 v140, v119, v140
	v_add_f32_e32 v140, v120, v140
	v_add_f32_e32 v140, v121, v140
	v_add_f32_e32 v140, v122, v140
	v_add_f32_e32 v140, v123, v140
	v_add_f32_e32 v140, v124, v140
	v_add_f32_e32 v140, v125, v140
	v_mfma_f32_32x32x16_bf16 v[48:63], v[164:167], v[182:185], v[48:63]
	v_add_f32_e32 v140, v126, v140
	v_cvt_pk_bf16_f32 v144, v112, v113
	v_cvt_pk_bf16_f32 v145, v114, v115
	v_cvt_pk_bf16_f32 v146, v116, v117
	v_cvt_pk_bf16_f32 v147, v118, v119
	v_mfma_f32_32x32x16_bf16 v[32:47], v[164:167], v[186:189], v[32:47]
	v_mfma_f32_32x32x16_bf16 v[16:31], v[164:167], v[214:217], v[16:31]
	v_add_f32_e32 v164, v127, v140
	v_cvt_pk_bf16_f32 v140, v120, v121
	v_cvt_pk_bf16_f32 v141, v122, v123
	v_cvt_pk_bf16_f32 v142, v124, v125
	v_cvt_pk_bf16_f32 v143, v126, v127
	v_mfma_f32_32x32x16_bf16 v[0:15], v[160:163], v[218:221], v[0:15]
	v_mfma_f32_32x32x16_bf16 v[48:63], v[160:163], v[222:225], v[48:63]
	v_mfma_f32_32x32x16_bf16 v[32:47], v[160:163], v[226:229], v[32:47]
	v_mfma_f32_32x32x16_bf16 v[16:31], v[160:163], v[230:233], v[16:31]
	v_add_u32_e32 v202, s100, v202
	v_add_u32_e32 v203, s100, v203
	v_subrev_u32_e32 v205, s100, v205
	v_subrev_u32_e32 v206, s100, v206
	v_subrev_u32_e32 v207, s101, v207
	s_sub_i32 s100, 0, s100
	s_sub_i32 s101, 0, s101
	s_cbranch_vccnz .LBB0_411
	s_mov_b64 s[8:9], s[6:7]
	s_branch .LBB0_398
